# grid barrier: all workgroups poll the TOP arrival counter directly (no TOPGEN / per-XCD generation hop)
# speedup vs baseline: 1.0152x; 1.0007x over previous
.LBB0_598:
	s_or_b64 exec, exec, s[2:3]
	v_cvt_f32_u32_e32 v4, v2
	s_waitcnt vmcnt(0)
	v_readfirstlane_b32 s2, v3
	v_sub_u32_e32 v3, 0, v2
	v_rcp_iflag_f32_e32 v4, v4
	v_add_u32_e32 v5, s2, v1
	v_mul_f32_e32 v4, 0x4f7ffffe, v4
	v_cvt_u32_f32_e32 v4, v4
	v_mul_lo_u32 v1, v3, v4
	v_mul_hi_u32 v1, v4, v1
	v_add_u32_e32 v1, v4, v1
	v_mul_hi_u32 v1, v5, v1
	v_mul_lo_u32 v3, v1, v2
	v_sub_u32_e32 v3, v5, v3
	v_add_u32_e32 v4, 1, v1
	v_cmp_ge_u32_e32 vcc, v3, v2
	s_nop 1
	v_cndmask_b32_e32 v1, v1, v4, vcc
	v_sub_u32_e32 v4, v3, v2
	v_cndmask_b32_e32 v3, v3, v4, vcc
	v_add_u32_e32 v4, 1, v1
	v_cmp_ge_u32_e32 vcc, v3, v2
	v_add_u32_e32 v3, 1, v5
	s_nop 0
	v_cndmask_b32_e32 v1, v1, v4, vcc
	v_mul_lo_u32 v4, v2, v1
	v_add_u32_e32 v2, v4, v2
	v_cmp_ne_u32_e32 vcc, v3, v2
	s_and_saveexec_b64 s[2:3], vcc
	s_xor_b64 s[2:3], exec, s[2:3]
	s_cbranch_execz .LBB0_612
	buffer_inv sc1
	v_readlane_b32 s6, v255, 32
	v_readlane_b32 s7, v255, 33
	s_waitcnt lgkmcnt(0)
	v_add_u32_e32 v6, 1, v1
	v_mul_lo_u32 v6, v0, v6
	s_nop 3
	global_load_dword v0, v177, s[6:7] sc1
	s_waitcnt vmcnt(0)
	v_cmp_lt_u32_e32 vcc, v0, v6
	s_and_saveexec_b64 s[6:7], vcc
	s_cbranch_execz .LBB0_611
	s_mov_b32 s12, 1
	s_mov_b64 s[8:9], 0
	s_branch .LBB0_602

.LBB0_604:
	v_readlane_b32 s20, v255, 32
	v_readlane_b32 s21, v255, 33
	s_add_i32 s12, s12, 1
	s_mov_b64 s[38:39], -1
	s_nop 2
	global_load_dword v0, v177, s[20:21] sc1
	s_waitcnt vmcnt(0)
	v_cmp_ge_u32_e32 vcc, v0, v6
	s_orn2_b64 s[36:37], vcc, exec
	s_branch .LBB0_601

.LBB0_615:
	s_or_b64 exec, exec, s[6:7]
	s_waitcnt vmcnt(0)
	v_readfirstlane_b32 s2, v2
	v_cvt_f32_u32_e32 v2, v0
	v_sub_u32_e32 v3, 0, v0
	v_add_u32_e32 v1, s2, v1
	v_readlane_b32 s2, v255, 34
	v_rcp_iflag_f32_e32 v2, v2
	v_readlane_b32 s3, v255, 35
	s_mov_b64 s[6:7], 0
	v_mul_f32_e32 v2, 0x4f7ffffe, v2
	v_cvt_u32_f32_e32 v2, v2
	v_mul_lo_u32 v3, v3, v2
	v_mul_hi_u32 v3, v2, v3
	v_add_u32_e32 v2, v2, v3
	v_mul_hi_u32 v2, v1, v2
	v_mul_lo_u32 v3, v2, v0
	v_sub_u32_e32 v3, v1, v3
	v_cmp_ge_u32_e32 vcc, v3, v0
	v_add_u32_e32 v4, 1, v2
	v_add_u32_e32 v1, 1, v1
	v_cndmask_b32_e32 v2, v2, v4, vcc
	v_sub_u32_e32 v4, v3, v0
	v_cndmask_b32_e32 v3, v3, v4, vcc
	v_cmp_ge_u32_e32 vcc, v3, v0
	v_add_u32_e32 v3, 1, v2
	s_nop 0
	v_cndmask_b32_e32 v2, v2, v3, vcc
	v_mul_lo_u32 v3, v0, v2
	v_add_u32_e32 v0, v3, v0
	v_mov_b32_e32 v6, v0
	v_cmp_ne_u32_e32 vcc, v1, v0
	v_mov_b64_e32 v[0:1], s[2:3]
	s_and_saveexec_b64 s[2:3], vcc
	s_cbranch_execz .LBB0_627
	v_readlane_b32 s6, v255, 32
	v_readlane_b32 s7, v255, 33
	s_mov_b64 s[8:9], 0
	s_nop 3
	global_load_dword v0, v177, s[6:7] sc1
	s_waitcnt vmcnt(0)
	v_cmp_lt_u32_e32 vcc, v0, v6
	s_and_saveexec_b64 s[6:7], vcc
	s_cbranch_execz .LBB0_626
	s_mov_b32 s12, 1
	s_branch .LBB0_619

.LBB0_629:
	s_or_b64 exec, exec, s[2:3]
	s_mov_b64 s[2:3], exec
	v_mbcnt_lo_u32_b32 v0, s2, 0
	v_mbcnt_hi_u32_b32 v0, s3, v0
	v_cmp_eq_u32_e32 vcc, 0, v0
	s_waitcnt vmcnt(0)
	buffer_inv sc1
	s_and_saveexec_b64 s[6:7], vcc
	s_cbranch_execz .LBB0_21
	s_bcnt1_i32_b64 s2, s[2:3]
	v_mov_b32_e32 v0, s2
	v_readlane_b32 s2, v255, 30
	v_readlane_b32 s3, v255, 31
	s_nop 4
	s_branch .LBB0_21
